# weight bf16 conversion for layers 1-3 moved from init into idle workgroups of phase E round 3 (re-entering the init transpose loop)
# speedup vs baseline: 1.0077x; 1.0077x over previous
; #define LAS __attribute__((address_space(3)))
; __global__ void __launch_bounds__(512, 2) mk_fwd(Args args) {
;     extern __shared__ __attribute__((aligned(16))) unsigned char lds_raw[];
;     cg::grid_group grid = cg::this_grid();
;     LAS unsigned char* lds = (LAS unsigned char*)lds_raw;
;     volatile LAS unsigned* xb_st = (volatile LAS unsigned*)(lds + LDS_BYTES - 64);
;     if (threadIdx.x == 0) { xb_st[0] = 0u; xb_st[1] = 0u; }
;     __syncthreads();
;     (void)xcd_barrier_post((unsigned*)(args.ws + WS_BAR), xb_st);
_Z6mk_fwd4Args:
	s_mov_b32 s101, 0
	s_load_dwordx8 s[4:11], s[0:1], 0xa0
	s_load_dword s20, s[0:1], 0xc0
	v_and_b32_e32 v252, 0x3ff, v0
	s_mov_b32 s67, s2
	v_cmp_eq_u32_e64 s[68:69], 0, v252
	s_waitcnt lgkmcnt(0)
	v_writelane_b32 v254, s4, 0
	s_nop 1
	v_writelane_b32 v254, s5, 1
	v_writelane_b32 v254, s6, 2
	v_writelane_b32 v254, s7, 3
	v_writelane_b32 v254, s8, 4
	v_writelane_b32 v254, s9, 5
	v_writelane_b32 v254, s10, 6
	v_writelane_b32 v254, s11, 7
	s_load_dwordx8 s[4:11], s[0:1], 0x80
	s_waitcnt lgkmcnt(0)
	v_writelane_b32 v254, s4, 8
	s_nop 1
	v_writelane_b32 v254, s5, 9
	v_writelane_b32 v254, s6, 10
	v_writelane_b32 v254, s7, 11
	v_writelane_b32 v254, s8, 12
	v_writelane_b32 v254, s9, 13
	v_writelane_b32 v254, s10, 14
	v_writelane_b32 v254, s11, 15
	s_add_u32 s8, s0, 0xb8
	s_addc_u32 s9, s1, 0
	s_and_saveexec_b64 s[2:3], s[68:69]
	s_cbranch_execz .LBB0_2
	s_add_i32 s4, 0, 0x23fc0
	v_mov_b32_e32 v1, 0
	v_mov_b32_e32 v2, s4
	s_add_i32 s4, 0, 0x23fc4
	ds_write_b32 v2, v1
	v_mov_b32_e32 v2, s4
	ds_write_b32 v2, v1

; __global__ void __launch_bounds__(512, 2) mk_fwd(Args args) {
;     ...
;         for (int it = gw; it < DEPTH * I_L; it += NGW) {
;             const int L = it / I_L; int r = it - L * I_L;
;             if (r < I_IN) { const int kb = r / 442, nb = r % 442, n0 = nb * 32;
;                 transpose_item(w_in + (size_t)L * DM * NIN, NIN, kb * 64, n0, nullptr, WIN + (size_t)L * NINP * DM, DM, n0 < NMIX ? n0 : n0 + (NMIXP - NMIX), scr, lane); continue; } r -= I_IN;
;             if (r < I_UQ) { const int kb = r / 48, nb = r % 48;
;                 transpose_item(w_uq + (size_t)L * 512 * 1536, 1536, kb * 64, nb * 32, qng + L * 512, WUQ + (size_t)L * 1536 * 512, 512, nb * 32, scr, lane); continue; } r -= I_UQ;
;             if (r < I_UKV) { const int kb = r / 64, nb = r % 64;
;                 transpose_item(w_ukv + (size_t)L * 256 * 2048, 2048, kb * 64, nb * 32, kvng + L * 256, WUKV + (size_t)L * 2048 * 256, 256, nb * 32, scr, lane); continue; } r -= I_UKV;
;             if (r < I_BR) { const int n3 = r / 1024, rr = r % 1024, kb = rr / 64, nb = rr % 64;
;                 transpose_item(w_branch + ((size_t)L * 3 + n3) * 1024 * 2048, 2048, kb * 64, nb * 32, nullptr, WBR + ((size_t)L * 3 + n3) * 2048 * 1024, 1024, nb * 32, scr, lane); continue; } r -= I_BR;
;             if (r < I_OUT) { const int kb = r / 64, nb = r % 64;
;                 transpose_item(w_out + (size_t)L * DM * DM, DM, kb * 64, nb * 32, nullptr, WOUT + (size_t)L * DM * DM, DM, nb * 32, scr, lane); continue; } r -= I_OUT;
;             { const int db = r / 4, nb = r % 4;
;               transpose_item(w_gate + ((size_t)L * 32 + db) * 64 * 128, 128, 0, nb * 32, nullptr, WG + ((size_t)L * 32 + db) * 128 * 64, 64, nb * 32, scr, lane); }
;         }
.Linit_reentry:
	v_mov_b32_e32 v6, v252
	s_mov_b32 s22, s67
	v_ashrrev_i32_e32 v10, 6, v6
	s_waitcnt lgkmcnt(0)
	v_writelane_b32 v254, s72, 18
	v_readfirstlane_b32 s0, v10
	v_and_b32_e32 v8, 63, v6
	v_writelane_b32 v254, s73, 19
	v_writelane_b32 v254, s74, 20
	v_writelane_b32 v254, s75, 21
	v_writelane_b32 v254, s76, 22
	v_writelane_b32 v254, s77, 23
	v_writelane_b32 v254, s78, 24
	v_writelane_b32 v254, s79, 25
	v_writelane_b32 v254, s80, 26
	v_writelane_b32 v254, s81, 27
	v_writelane_b32 v254, s82, 28
	v_writelane_b32 v254, s83, 29
	v_writelane_b32 v254, s84, 30
	v_writelane_b32 v254, s85, 31
	v_writelane_b32 v254, s86, 32
	v_writelane_b32 v254, s87, 33
	s_nop 0
	v_readlane_b32 s24, v254, 0
	v_readlane_b32 s25, v254, 1
	v_readlane_b32 s26, v254, 2
	v_readlane_b32 s27, v254, 3
	v_readlane_b32 s28, v254, 4
	v_readlane_b32 s29, v254, 5
	v_readlane_b32 s30, v254, 6
	v_readlane_b32 s31, v254, 7
	v_writelane_b32 v254, s40, 34
	s_mov_b32 s21, s30
	s_lshl_b32 s1, s22, 3
	v_writelane_b32 v254, s41, 35
	v_writelane_b32 v254, s42, 36
	v_writelane_b32 v254, s43, 37
	v_writelane_b32 v254, s44, 38
	v_writelane_b32 v254, s45, 39
	v_writelane_b32 v254, s46, 40
	v_writelane_b32 v254, s47, 41
	v_writelane_b32 v254, s48, 42
	v_writelane_b32 v254, s49, 43
	v_writelane_b32 v254, s50, 44
	v_writelane_b32 v254, s51, 45
	s_add_i32 s16, s1, s0
	s_mov_b32 s1, 0
	v_writelane_b32 v254, s52, 46
	s_add_u32 s6, s28, s1
	v_writelane_b32 v254, s53, 47
	s_addc_u32 s7, s29, 0
	v_writelane_b32 v254, s54, 48
	s_cmp_lg_u32 s101, 0
	s_cbranch_scc1 .Linit_bound_done
	s_mov_b32 s100, 0x138ff
	s_cmpk_lg_u32 s21, 0x100
	s_cbranch_scc1 .Linit_bound_done
	s_movk_i32 s100, 0x4e3f
.Linit_bound_done:
	s_cmp_gt_i32 s16, s100
	s_mov_b32 s1, 0
	v_writelane_b32 v254, s55, 49
	s_cbranch_scc1 .LBB0_72
	s_mul_i32 s12, s0, 0x2100
	s_lshl_b32 s17, s21, 3
	s_add_i32 s4, s12, 0
	s_add_u32 s19, s6, 0x11a00000
	s_addc_u32 s23, s7, 0
	s_add_u32 s24, s6, 0xea00000
	v_lshlrev_b32_e32 v1, 3, v8
	s_addc_u32 s25, s7, 0
	v_and_b32_e32 v14, 56, v1
	s_add_u32 s26, s6, 0xe600000
	v_readlane_b32 s72, v254, 18
	v_and_b32_e32 v26, 31, v6
	v_mov_b32_e32 v5, 0
	v_lshrrev_b32_e32 v3, 3, v8
	v_lshlrev_b32_e32 v4, 1, v14
	s_addc_u32 s27, s7, 0
	v_readlane_b32 s74, v254, 20
	v_readlane_b32 s75, v254, 21
	v_lshlrev_b32_e32 v22, 2, v26
	v_mul_u32_u24_e32 v1, 0x84, v14
	v_lshl_add_u64 v[16:17], s[6:7], 0, v[4:5]
	v_lshlrev_b32_e32 v4, 2, v3
	s_cmp_lg_u64 s[74:75], 0
	v_lshrrev_b32_e32 v2, 5, v8
	v_add_u32_e32 v12, s4, v22
	v_add3_u32 v7, s4, v1, v4
	s_cselect_b64 s[4:5], -1, 0
	s_add_u32 s28, s6, 0xe000000
	v_readlane_b32 s73, v254, 19
	s_addc_u32 s29, s7, 0
	v_mul_u32_u24_e32 v4, 0x84, v2
	s_mov_b64 s[2:3], 0x13a00000
	s_cmp_lg_u64 s[72:73], 0
	v_or_b32_e32 v4, s12, v4
	v_lshl_add_u64 v[16:17], v[16:17], 0, s[2:3]
	v_readlane_b32 s76, v254, 22
	v_readlane_b32 s77, v254, 23
	v_readlane_b32 s78, v254, 24
	v_readlane_b32 s79, v254, 25
	s_cselect_b64 s[10:11], -1, 0
	v_add3_u32 v15, v4, v22, 0
	v_mov_b32_e32 v23, v5
	s_lshl_b32 s2, s22, 8
	s_lshl_b32 s0, s0, 5
	v_mul_u32_u24_e32 v4, 0x1800, v2
	v_lshl_add_u64 v[18:19], s[78:79], 0, v[22:23]
	s_add_i32 s30, s2, s0
	s_lshl_b32 s31, s21, 8
	v_lshl_add_u64 v[20:21], s[76:77], 0, v[22:23]
	v_or_b32_e32 v22, v4, v22
	v_lshlrev_b32_e32 v4, 2, v2
	s_add_u32 s33, s74, 0xffff1d20
	v_mul_hi_u32_u24_e32 v23, 0x1800, v2
	v_lshl_add_u64 v[24:25], s[72:73], 0, v[4:5]
	s_movk_i32 s18, 0x84
	v_or_b32_e32 v9, 8, v3
	v_or_b32_e32 v11, 16, v3
	v_or_b32_e32 v13, 24, v3
	v_mov_b32_e32 v1, v2
	v_or_b32_e32 v48, 0xffffc74e, v2
	v_or_b32_e32 v49, 0xffffc740, v2
	v_or_b32_e32 v50, 0xffffc74c, v2
	v_or_b32_e32 v51, 0xffffc74a, v2
	v_or_b32_e32 v52, 0xffffc742, v2
	v_or_b32_e32 v53, 0xffffc748, v2
	s_addc_u32 s34, s75, -1
	v_or_b32_e32 v54, 0xffffc746, v2
	v_or_b32_e32 v55, 0xffffc744, v2
	v_or_b32_e32 v56, 14, v2
	v_lshl_add_u64 v[22:23], s[76:77], 0, v[22:23]
	v_or_b32_e32 v57, 12, v2
	v_lshl_add_u64 v[24:25], v[24:25], 0, 56
	v_or_b32_e32 v58, 10, v2
	v_or_b32_e32 v59, 8, v2
	v_or_b32_e32 v60, 6, v2
	v_or_b32_e32 v61, 4, v2
	v_or_b32_e32 v62, 2, v2
	s_mov_b32 s35, 0xdd00
	v_lshlrev_b32_e32 v26, 2, v26
	v_readlane_b32 s80, v254, 26
	v_readlane_b32 s81, v254, 27
	v_readlane_b32 s82, v254, 28
	v_readlane_b32 s83, v254, 29
	v_readlane_b32 s84, v254, 30
	v_readlane_b32 s85, v254, 31
	v_readlane_b32 s86, v254, 32
	v_readlane_b32 s87, v254, 33
	s_cmp_eq_u32 s101, 0
	s_cbranch_scc1 .Linit_go
	s_mul_i32 s16, s101, 0x4e40
	s_add_i32 s16, s16, s99
	s_lshl_b32 s30, s16, 5
	s_movk_i32 s17, 0x600
	s_mov_b32 s31, 0xc000
.Linit_go:
	s_branch .LBB0_8
.LBB0_7:
	s_add_i32 s16, s16, s17
	s_add_i32 s30, s30, s31
	s_cmp_gt_i32 s16, s100
	s_cbranch_scc1 .LBB0_72

; __global__ void __launch_bounds__(512, 2) mk_fwd(Args args) {
;     ...
;         for (int i = bid * 512 + tid; i < DEPTH * (NMIXP - NMIX) * (DM / 8); i += G * 512) {
;             const int L = i / ((NMIXP - NMIX) * (DM / 8)), r = i % ((NMIXP - NMIX) * (DM / 8));
;             *(u32x4*)(WIN + ((size_t)L * NINP + NMIX) * DM + (size_t)r * 8) = (u32x4){0u, 0u, 0u, 0u};
;         }
.LBB0_72:
	s_cmp_lg_u32 s101, 0
	s_cbranch_scc1 .Ltramp_ret
	v_lshl_add_u32 v1, s22, 9, v6
	s_mov_b32 s0, 0x30000
	v_cmp_gt_i32_e32 vcc, s0, v1
	s_and_saveexec_b64 s[0:1], vcc
	s_cbranch_execz .LBB0_75
	v_mov_b32_e32 v2, 0
	s_lshl_b32 s4, s21, 9
	s_mov_b64 s[2:3], 0
	s_mov_b32 s5, 0x2aaaaaab
	v_mov_b32_e32 v3, v2
	v_mov_b32_e32 v4, v2
	v_mov_b32_e32 v5, v2
	s_mov_b32 s10, 0x2ffff

; #define PG8_WAIT_V(n) asm volatile("s_waitcnt vmcnt(" #n ")" ::: "memory")
; #define PG8_BAR __builtin_amdgcn_s_barrier()
; #define EPI_FENCE(a, b) asm volatile("" : "+v"(a), "+v"(b) :: "memory")
; template <class Epi>
; __device__ __forceinline__ void gemm_phase(LAS unsigned char* lds, const Gemm g, const Sched& S, const Epi& E) {
;     ...
;     PG8_WAIT_V(0);
;     PG8_BAR;
;     __device__ __forceinline__ void operator()(const AccT& acc, const pg8::Unit& u, int wr, int wc, int fr, int fq) const {
;     ...
; #pragma unroll
;             for (int i = 0; i < 4; ++i) { const int m = m0 + (i >> 1), bj = i & 1; const int row = row0 + ai * 128 + m * 16, col0 = pn * 256 + bj * 128 + wc * 32 + 8 * fq;
;                 f32x4 v0 = acc[ai][bj][m][0], v1 = acc[ai][bj][m][1]; EPI_FENCE(v0, v1);
;                 const f32x4 g0 = *(const f32x4*)(gt + col0), g1 = *(const f32x4*)(gt + col0 + 4);
;                 *(f32x4*)(xcur + (size_t)row * 2048 + col0) = xa[i] + g0 * v0;
;                 *(f32x4*)(xcur + (size_t)row * 2048 + col0 + 4) = xb[i] + g1 * v1; }
.LBB0_914:
	v_lshl_add_u64 v[64:65], v[64:65], 0, v[152:153]
	global_load_dwordx4 v[60:63], v[64:65], off offset:528
	s_nop 0
	global_load_dwordx4 v[64:67], v[64:65], off offset:512
	global_load_dwordx4 v[68:71], v[154:155], off offset:16
	global_load_dwordx4 v[72:75], v[154:155], off
	v_ashrrev_i32_e32 v57, 31, v56
	s_waitcnt vmcnt(1)
	v_pk_fma_f32 v[24:25], v[24:25], v[68:69], v[44:45]
	s_waitcnt vmcnt(0)
	v_pk_fma_f32 v[28:29], v[72:73], v[28:29], v[52:53]
	v_lshlrev_b64 v[52:53], 13, v[56:57]
	v_lshl_add_u64 v[52:53], s[0:1], 0, v[52:53]
	v_pk_fma_f32 v[30:31], v[74:75], v[30:31], v[54:55]
	v_lshl_add_u64 v[52:53], v[52:53], 0, v[152:153]
	v_pk_fma_f32 v[26:27], v[26:27], v[70:71], v[46:47]
	global_store_dwordx4 v[52:53], v[28:31], off
	global_store_dwordx4 v[52:53], v[24:27], off offset:16
	global_load_dwordx4 v[24:27], v[120:121], off offset:16
	global_load_dwordx4 v[28:31], v[120:121], off
	s_waitcnt vmcnt(1)
	v_pk_fma_f32 v[12:13], v[12:13], v[24:25], v[32:33]
	s_waitcnt vmcnt(0)
	v_pk_fma_f32 v[22:23], v[30:31], v[22:23], v[38:39]
	v_pk_fma_f32 v[20:21], v[28:29], v[20:21], v[36:37]
	v_pk_fma_f32 v[14:15], v[14:15], v[26:27], v[34:35]
	global_store_dwordx4 v[52:53], v[20:23], off offset:512
	global_store_dwordx4 v[52:53], v[12:15], off offset:528
	global_load_dwordx4 v[12:15], v[154:155], off offset:16
	global_load_dwordx4 v[20:23], v[154:155], off
	s_waitcnt vmcnt(1)
	v_pk_fma_f32 v[8:9], v[8:9], v[12:13], v[40:41]
	s_waitcnt vmcnt(0)
	v_pk_fma_f32 v[16:17], v[20:21], v[16:17], v[48:49]
	v_lshl_add_u64 v[20:21], s[0:1], 0, v[58:59]
	v_pk_fma_f32 v[18:19], v[22:23], v[18:19], v[50:51]
	v_lshl_add_u64 v[20:21], v[20:21], 0, v[152:153]
	v_pk_fma_f32 v[10:11], v[10:11], v[14:15], v[42:43]
	global_store_dwordx4 v[20:21], v[16:19], off
	global_store_dwordx4 v[20:21], v[8:11], off offset:16
	global_load_dwordx4 v[8:11], v[120:121], off offset:16
	global_load_dwordx4 v[12:15], v[120:121], off
	s_waitcnt vmcnt(1)
	v_pk_fma_f32 v[2:3], v[2:3], v[10:11], v[62:63]
	s_waitcnt vmcnt(0)
	v_pk_fma_f32 v[6:7], v[14:15], v[6:7], v[66:67]
	v_pk_fma_f32 v[4:5], v[12:13], v[4:5], v[64:65]
	v_pk_fma_f32 v[0:1], v[0:1], v[8:9], v[60:61]
	global_store_dwordx4 v[20:21], v[4:7], off offset:512
	global_store_dwordx4 v[20:21], v[0:3], off offset:528
	s_waitcnt vmcnt(0)
	s_barrier
	s_branch .LBB0_915
.Lconv_check:
	s_cmp_lg_u64 s[6:7], 0
	s_cbranch_scc0 .LBB0_915
	s_cmp_lt_u32 s41, 32
	s_cbranch_scc1 .LBB0_915
	v_readfirstlane_b32 s98, v252
	v_readlane_b32 s101, v255, 20
	s_sub_i32 s99, s41, 32
	s_sub_i32 s100, s41, 64
	s_cmp_lt_u32 s41, 128
	s_cselect_b32 s99, s99, s100
	s_lshl_b32 s99, s99, 3
	s_lshr_b32 s98, s98, 6
	s_add_i32 s99, s99, s98
	v_writelane_b32 v253, s4, 0
	v_writelane_b32 v253, s5, 1
	v_writelane_b32 v253, s6, 2
	v_writelane_b32 v253, s7, 3
	v_writelane_b32 v253, s10, 4
	v_writelane_b32 v253, s11, 5
	v_writelane_b32 v253, s12, 6
	v_writelane_b32 v253, s13, 7
	v_writelane_b32 v253, s14, 8
	v_writelane_b32 v253, s15, 9
	v_writelane_b32 v253, s16, 10
	v_writelane_b32 v253, s17, 11
	v_writelane_b32 v253, s18, 12
	v_writelane_b32 v253, s19, 13
	v_writelane_b32 v253, s21, 14
	v_writelane_b32 v253, s22, 15
	v_writelane_b32 v253, s23, 16
	v_writelane_b32 v253, s24, 17
	v_writelane_b32 v253, s25, 18
	v_writelane_b32 v253, s26, 19
	v_writelane_b32 v253, s33, 20
	v_writelane_b32 v253, s73, 21
	v_writelane_b32 v253, s74, 22
	v_writelane_b32 v253, s75, 23
	v_writelane_b32 v253, s76, 24
	v_writelane_b32 v253, s77, 25
	v_writelane_b32 v253, vcc_lo, 26
	v_writelane_b32 v253, vcc_hi, 27
	s_add_i32 s101, s101, 1
	s_mul_i32 s100, s101, 0x4e40
	s_addk_i32 s100, 0x4e3f
	v_readlane_b32 s40, v254, 34
	v_readlane_b32 s41, v254, 35
	v_readlane_b32 s42, v254, 36
	v_readlane_b32 s43, v254, 37
	v_readlane_b32 s44, v254, 38
	v_readlane_b32 s45, v254, 39
	v_readlane_b32 s46, v254, 40
	v_readlane_b32 s47, v254, 41
	v_readlane_b32 s48, v254, 42
	v_readlane_b32 s49, v254, 43
	v_readlane_b32 s50, v254, 44
	v_readlane_b32 s51, v254, 45
	v_readlane_b32 s52, v254, 46
	v_readlane_b32 s53, v254, 47
	v_readlane_b32 s54, v254, 48
	v_readlane_b32 s55, v254, 49
	v_readlane_b32 s72, v254, 18
	v_readlane_b32 s73, v254, 19
	v_readlane_b32 s74, v254, 20
	v_readlane_b32 s75, v254, 21
	v_readlane_b32 s76, v254, 22
	v_readlane_b32 s77, v254, 23
	v_readlane_b32 s78, v254, 24
	v_readlane_b32 s79, v254, 25
	v_readlane_b32 s80, v254, 26
	v_readlane_b32 s81, v254, 27
	v_readlane_b32 s82, v254, 28
	v_readlane_b32 s83, v254, 29
	v_readlane_b32 s84, v254, 30
	v_readlane_b32 s85, v254, 31
	v_readlane_b32 s86, v254, 32
	v_readlane_b32 s87, v254, 33
	s_nop 4
	s_branch .Ltramp_call
.Lconv_return:
	v_readlane_b32 s4, v253, 0
	v_readlane_b32 s5, v253, 1
	v_readlane_b32 s6, v253, 2
	v_readlane_b32 s7, v253, 3
	v_readlane_b32 s10, v253, 4
	v_readlane_b32 s11, v253, 5
	v_readlane_b32 s12, v253, 6
	v_readlane_b32 s13, v253, 7
	v_readlane_b32 s14, v253, 8
	v_readlane_b32 s15, v253, 9
	v_readlane_b32 s16, v253, 10
	v_readlane_b32 s17, v253, 11
	v_readlane_b32 s18, v253, 12
	v_readlane_b32 s19, v253, 13
	v_readlane_b32 s21, v253, 14
	v_readlane_b32 s22, v253, 15
	v_readlane_b32 s23, v253, 16
	v_readlane_b32 s24, v253, 17
	v_readlane_b32 s25, v253, 18
	v_readlane_b32 s26, v253, 19
	v_readlane_b32 s33, v253, 20
	v_readlane_b32 s73, v253, 21
	v_readlane_b32 s74, v253, 22
	v_readlane_b32 s75, v253, 23
	v_readlane_b32 s76, v253, 24
	v_readlane_b32 s77, v253, 25
	v_readlane_b32 vcc_lo, v253, 26
	v_readlane_b32 vcc_hi, v253, 27
	s_mov_b32 s101, 0
	s_nop 4

; __global__ void __launch_bounds__(512, 2) mk_fwd(Args args) {
	.amdhsa_kernel _Z6mk_fwd4Args
		.amdhsa_group_segment_fixed_size 0
		.amdhsa_private_segment_fixed_size 0
		.amdhsa_kernarg_size 440
		.amdhsa_user_sgpr_count 2
		.amdhsa_user_sgpr_dispatch_ptr 0
		.amdhsa_user_sgpr_queue_ptr 0
		.amdhsa_user_sgpr_kernarg_segment_ptr 1
		.amdhsa_user_sgpr_dispatch_id 0
		.amdhsa_user_sgpr_kernarg_preload_length 0
		.amdhsa_user_sgpr_kernarg_preload_offset 0
		.amdhsa_user_sgpr_private_segment_size 0
		.amdhsa_uses_dynamic_stack 0
		.amdhsa_enable_private_segment 0
		.amdhsa_system_sgpr_workgroup_id_x 1
		.amdhsa_system_sgpr_workgroup_id_y 0
		.amdhsa_system_sgpr_workgroup_id_z 0
		.amdhsa_system_sgpr_workgroup_info 0
		.amdhsa_system_vgpr_workitem_id 2
		.amdhsa_next_free_vgpr 256
		.amdhsa_next_free_sgpr 102
		.amdhsa_accum_offset 256
		.amdhsa_reserve_vcc 1
		.amdhsa_float_round_mode_32 0
		.amdhsa_float_round_mode_16_64 0
		.amdhsa_float_denorm_mode_32 3
		.amdhsa_float_denorm_mode_16_64 3
		.amdhsa_dx10_clamp 1
		.amdhsa_ieee_mode 1
		.amdhsa_fp16_overflow 0
		.amdhsa_tg_split 0
		.amdhsa_exception_fp_ieee_invalid_op 0
		.amdhsa_exception_fp_denorm_src 0
		.amdhsa_exception_fp_ieee_div_zero 0
		.amdhsa_exception_fp_ieee_overflow 0
		.amdhsa_exception_fp_ieee_underflow 0
		.amdhsa_exception_fp_ieee_inexact 0
		.amdhsa_exception_int_div_zero 0
	.end_amdhsa_kernel

; __global__ void __launch_bounds__(512, 2) mk_fwd(Args args) {
amdhsa.kernels:
  - .agpr_count:     0
    .args:
      - .offset:         0
        .size:           184
        .value_kind:     by_value
      - .offset:         184
        .size:           4
        .value_kind:     hidden_block_count_x
      - .offset:         188
        .size:           4
        .value_kind:     hidden_block_count_y
      - .offset:         192
        .size:           4
        .value_kind:     hidden_block_count_z
      - .offset:         196
        .size:           2
        .value_kind:     hidden_group_size_x
      - .offset:         198
        .size:           2
        .value_kind:     hidden_group_size_y
      - .offset:         200
        .size:           2
        .value_kind:     hidden_group_size_z
      - .offset:         202
        .size:           2
        .value_kind:     hidden_remainder_x
      - .offset:         204
        .size:           2
        .value_kind:     hidden_remainder_y
      - .offset:         206
        .size:           2
        .value_kind:     hidden_remainder_z
      - .offset:         224
        .size:           8
        .value_kind:     hidden_global_offset_x
      - .offset:         232
        .size:           8
        .value_kind:     hidden_global_offset_y
      - .offset:         240
        .size:           8
        .value_kind:     hidden_global_offset_z
      - .offset:         248
        .size:           2
        .value_kind:     hidden_grid_dims
      - .offset:         272
        .size:           8
        .value_kind:     hidden_multigrid_sync_arg
      - .offset:         304
        .size:           4
        .value_kind:     hidden_dynamic_lds_size
    .group_segment_fixed_size: 0
    .kernarg_segment_align: 8
    .kernarg_segment_size: 440
    .language:       OpenCL C
    .language_version:
      - 2
      - 0
    .max_flat_workgroup_size: 512
    .name:           _Z6mk_fwd4Args
    .private_segment_fixed_size: 0
    .sgpr_count:     108
    .sgpr_spill_count: 111
    .symbol:         _Z6mk_fwd4Args.kd
    .uniform_work_group_size: 1
    .uses_dynamic_stack: false
    .vgpr_count:     256
    .vgpr_spill_count: 0
    .wavefront_size: 64
